# P0 weight re-layout in registers with a DPP half-swap so every store writes whole 128-byte lines
# speedup vs baseline: 1.0069x; 1.0069x over previous
; #define LAS __attribute__((address_space(3)))
; __device__ __forceinline__ void p0_item(const float* W, int ldw, int col0, int k0, const float* gain, bf16_t* WT, int K, int drow0, LAS float* scr, int lane) {
;     float v[64];
;     const float* src = W + (size_t)k0 * ldw + col0 + lane;
; #pragma unroll
;     for (int i = 0; i < 64; ++i) v[i] = src[(size_t)i * ldw];
;     const int c = lane & 7;
; __global__ void __launch_bounds__(NWAVES * 64, 2) fwd_megakernel(Args args) {
;     ...
;         LAS float* scr = (LAS float*)(lds + wave * 16640);
;         constexpr int I_GU = (DM / 64) * (FF / 64), I_DN = (FF / 64) * (DM / 64), I_IN = (DM / 64) * (1024 / 64), I_SQ = (DM / 64) * (DM / 64), I_PP = (PLE / 64) * (DM / 64);
;         constexpr int NITEMS = 4 * I_GU + 2 * I_DN + 6 * I_IN + 2 * I_SQ + I_PP;
;         for (int it = gw; it < NITEMS; it += NGW) {
.LBB0_28:
	v_writelane_b32 v250, s30, 30
	s_nop 1
	v_writelane_b32 v250, s31, 31
	v_writelane_b32 v250, s27, 32
	s_or_b64 exec, exec, s[4:5]
	s_lshr_b32 s64, s3, 6
	s_lshl_b32 s1, s26, 3
	s_add_i32 s1, s1, s64
	s_add_u32 s4, s60, 0x200000
	s_addc_u32 s5, s61, 0
	v_writelane_b32 v250, s4, 34
	v_and_b32_e32 v168, 63, v166
	s_nop 0
	v_writelane_b32 v250, s5, 35
	s_add_u32 s4, s60, 0x2e00000
	s_addc_u32 s5, s61, 0
	v_writelane_b32 v250, s4, 36
	s_nop 1
	v_writelane_b32 v250, s5, 37
	s_add_u32 s4, s60, 0x4400000
	s_addc_u32 s5, s61, 0
	v_writelane_b32 v250, s4, 38
	s_nop 1
	v_writelane_b32 v250, s5, 39
	s_add_u32 s4, s60, 0x5400000
	s_addc_u32 s5, s61, 0
	v_writelane_b32 v250, s4, 40
	s_nop 1
	v_writelane_b32 v250, s5, 41
	s_add_u32 s4, s60, 0x5c00000
	s_addc_u32 s5, s61, 0
	v_writelane_b32 v250, s4, 42
	s_nop 1
	v_writelane_b32 v250, s5, 43
	s_add_u32 s4, s60, 0x6400000
	s_addc_u32 s5, s61, 0
	v_writelane_b32 v250, s4, 44
	s_nop 1
	v_writelane_b32 v250, s5, 45
	s_add_u32 s4, s60, 0x9000000
	s_addc_u32 s5, s61, 0
	v_writelane_b32 v250, s4, 46
	s_nop 1
	v_writelane_b32 v250, s5, 47
	s_add_u32 s4, s60, 0xa600000
	s_addc_u32 s5, s61, 0
	v_writelane_b32 v250, s4, 48
	s_nop 1
	v_writelane_b32 v250, s5, 49
	s_add_u32 s4, s60, 0xae00000
	s_addc_u32 s5, s61, 0
	v_writelane_b32 v250, s4, 50
	s_cmpk_gt_i32 s1, 0x567f
	s_nop 0
	v_writelane_b32 v250, s5, 51
	v_writelane_b32 v250, s1, 52
	s_cbranch_scc1 .LBB0_120
	v_lshrrev_b32_e32 v85, 4, v168
	v_and_b32_e32 v86, 15, v168
	v_lshlrev_b32_e32 v87, 4, v86
	v_lshlrev_b32_e32 v67, 5, v85
	v_lshlrev_b32_e32 v88, 4, v85
	v_xor_b32_e32 v90, 7, v86
	v_and_b32_e32 v91, 4, v86
	v_cmp_eq_u32_e32 vcc, 0, v91
	s_nop 1
	v_cndmask_b32_e32 v92, v90, v86, vcc
	v_cndmask_b32_e32 v93, v86, v90, vcc
	v_lshlrev_b32_e32 v92, 2, v92
	v_lshlrev_b32_e32 v93, 2, v93
	v_add_u32_e32 v94, v85, v91
	v_lshlrev_b32_e32 v94, 4, v94
	v_readlane_b32 s55, v250, 52
	s_lshl_b32 s1, s62, 3

; __device__ __forceinline__ void p0_item(const float* W, int ldw, int col0, int k0, const float* gain, bf16_t* WT, int K, int drow0, LAS float* scr, int lane) {
;     ...
;     const float* src = W + (size_t)k0 * ldw + col0 + lane;
; #pragma unroll
;     for (int i = 0; i < 64; ++i) v[i] = src[(size_t)i * ldw];
;     const int c = lane & 7;
;     f32x4 g0 = {1.f, 1.f, 1.f, 1.f}, g1 = {1.f, 1.f, 1.f, 1.f};
;     if (gain) { g0 = *(const f32x4*)(gain + k0 + 8 * c); g1 = *(const f32x4*)(gain + k0 + 8 * c + 4); }
.Lp0_rows:
	s_mul_i32 s4, s33, s30
	s_add_u32 s4, s4, s31
	s_lshl_b32 s4, s4, 2
	s_add_u32 s40, s28, s4
	s_addc_u32 s41, s29, 0
	s_lshl_b32 s5, s30, 2
	s_lshl_b32 s6, s5, 3
	v_mul_lo_u32 v66, v85, s6
	v_add_u32_e32 v66, v66, v87
	s_mul_i32 s6, s5, 25
	global_load_dwordx4 v[2:5], v66, s[40:41]
	s_add_u32 s40, s40, s5
	s_addc_u32 s41, s41, 0
	global_load_dwordx4 v[6:9], v66, s[40:41]
	s_add_u32 s40, s40, s5
	s_addc_u32 s41, s41, 0
	global_load_dwordx4 v[10:13], v66, s[40:41]
	s_add_u32 s40, s40, s5
	s_addc_u32 s41, s41, 0
	global_load_dwordx4 v[14:17], v66, s[40:41]
	s_add_u32 s40, s40, s5
	s_addc_u32 s41, s41, 0
	global_load_dwordx4 v[18:21], v66, s[40:41]
	s_add_u32 s40, s40, s5
	s_addc_u32 s41, s41, 0
	global_load_dwordx4 v[22:25], v66, s[40:41]
	s_add_u32 s40, s40, s5
	s_addc_u32 s41, s41, 0
	global_load_dwordx4 v[26:29], v66, s[40:41]
	s_add_u32 s40, s40, s5
	s_addc_u32 s41, s41, 0
	global_load_dwordx4 v[30:33], v66, s[40:41]
	s_add_u32 s40, s40, s6
	s_addc_u32 s41, s41, 0
	global_load_dwordx4 v[34:37], v66, s[40:41]
	s_add_u32 s40, s40, s5
	s_addc_u32 s41, s41, 0
	global_load_dwordx4 v[38:41], v66, s[40:41]
	s_add_u32 s40, s40, s5
	s_addc_u32 s41, s41, 0
	global_load_dwordx4 v[42:45], v66, s[40:41]
	s_add_u32 s40, s40, s5
	s_addc_u32 s41, s41, 0
	global_load_dwordx4 v[46:49], v66, s[40:41]
	s_add_u32 s40, s40, s5
	s_addc_u32 s41, s41, 0
	global_load_dwordx4 v[50:53], v66, s[40:41]
	s_add_u32 s40, s40, s5
	s_addc_u32 s41, s41, 0
	global_load_dwordx4 v[54:57], v66, s[40:41]
	s_add_u32 s40, s40, s5
	s_addc_u32 s41, s41, 0
	global_load_dwordx4 v[58:61], v66, s[40:41]
	s_add_u32 s40, s40, s5
	s_addc_u32 s41, s41, 0
	global_load_dwordx4 v[62:65], v66, s[40:41]
	s_mul_i32 s4, s39, s38
	s_add_u32 s4, s4, s33
	s_lshl_b32 s4, s4, 1
	s_add_u32 s44, s36, s4
	s_addc_u32 s45, s37, 0
	s_lshl_b32 s6, s38, 1
	v_mul_lo_u32 v84, v92, s6
	v_mul_lo_u32 v95, v93, s6
	v_add_u32_e32 v84, v84, v94
	v_add_u32_e32 v95, v95, v94
	s_waitcnt vmcnt(15)
	v_pk_mul_f32 v[2:3], v[2:3], v[68:69] op_sel_hi:[1,0]
	v_pk_mul_f32 v[4:5], v[4:5], v[68:69] op_sel_hi:[1,0]
	s_waitcnt vmcnt(14)
	v_pk_mul_f32 v[6:7], v[6:7], v[68:69] op_sel:[0,1] op_sel_hi:[1,1]
	v_pk_mul_f32 v[8:9], v[8:9], v[68:69] op_sel:[0,1] op_sel_hi:[1,1]
	s_waitcnt vmcnt(13)
	v_pk_mul_f32 v[10:11], v[10:11], v[70:71] op_sel_hi:[1,0]
	v_pk_mul_f32 v[12:13], v[12:13], v[70:71] op_sel_hi:[1,0]
	s_waitcnt vmcnt(12)
	v_pk_mul_f32 v[14:15], v[14:15], v[70:71] op_sel:[0,1] op_sel_hi:[1,1]
	v_pk_mul_f32 v[16:17], v[16:17], v[70:71] op_sel:[0,1] op_sel_hi:[1,1]
	s_waitcnt vmcnt(11)
	v_pk_mul_f32 v[18:19], v[18:19], v[72:73] op_sel_hi:[1,0]
	v_pk_mul_f32 v[20:21], v[20:21], v[72:73] op_sel_hi:[1,0]
	s_waitcnt vmcnt(10)
	v_pk_mul_f32 v[22:23], v[22:23], v[72:73] op_sel:[0,1] op_sel_hi:[1,1]
	v_pk_mul_f32 v[24:25], v[24:25], v[72:73] op_sel:[0,1] op_sel_hi:[1,1]
	s_waitcnt vmcnt(9)
	v_pk_mul_f32 v[26:27], v[26:27], v[74:75] op_sel_hi:[1,0]
	v_pk_mul_f32 v[28:29], v[28:29], v[74:75] op_sel_hi:[1,0]
	s_waitcnt vmcnt(8)
	v_pk_mul_f32 v[30:31], v[30:31], v[74:75] op_sel:[0,1] op_sel_hi:[1,1]
	v_pk_mul_f32 v[32:33], v[32:33], v[74:75] op_sel:[0,1] op_sel_hi:[1,1]
	s_waitcnt vmcnt(7)
	v_pk_mul_f32 v[34:35], v[34:35], v[76:77] op_sel_hi:[1,0]
	v_pk_mul_f32 v[36:37], v[36:37], v[76:77] op_sel_hi:[1,0]
	s_waitcnt vmcnt(6)
	v_pk_mul_f32 v[38:39], v[38:39], v[76:77] op_sel:[0,1] op_sel_hi:[1,1]
	v_pk_mul_f32 v[40:41], v[40:41], v[76:77] op_sel:[0,1] op_sel_hi:[1,1]
	s_waitcnt vmcnt(5)
	v_pk_mul_f32 v[42:43], v[42:43], v[78:79] op_sel_hi:[1,0]
	v_pk_mul_f32 v[44:45], v[44:45], v[78:79] op_sel_hi:[1,0]
	s_waitcnt vmcnt(4)
	v_pk_mul_f32 v[46:47], v[46:47], v[78:79] op_sel:[0,1] op_sel_hi:[1,1]
	v_pk_mul_f32 v[48:49], v[48:49], v[78:79] op_sel:[0,1] op_sel_hi:[1,1]
	s_waitcnt vmcnt(3)
	v_pk_mul_f32 v[50:51], v[50:51], v[80:81] op_sel_hi:[1,0]
	v_pk_mul_f32 v[52:53], v[52:53], v[80:81] op_sel_hi:[1,0]
	s_waitcnt vmcnt(2)
	v_pk_mul_f32 v[54:55], v[54:55], v[80:81] op_sel:[0,1] op_sel_hi:[1,1]
	v_pk_mul_f32 v[56:57], v[56:57], v[80:81] op_sel:[0,1] op_sel_hi:[1,1]
	s_waitcnt vmcnt(1)
	v_pk_mul_f32 v[58:59], v[58:59], v[82:83] op_sel_hi:[1,0]
	v_pk_mul_f32 v[60:61], v[60:61], v[82:83] op_sel_hi:[1,0]
	s_waitcnt vmcnt(0)
; #define LAS __attribute__((address_space(3)))
; __device__ __forceinline__ unsigned cvtpk(float lo, float hi) { f32x2 v = {lo, hi}; bf16x2_t b = __builtin_convertvector(v, bf16x2_t); return __builtin_bit_cast(unsigned, b); }
; __device__ __forceinline__ void p0_item(const float* W, int ldw, int col0, int k0, const float* gain, bf16_t* WT, int K, int drow0, LAS float* scr, int lane) {
;     ...
;     for (int j = 0; j < 8; ++j) { const int n = (lane >> 3) + 8 * j; const LAS float* s = scr + (8 * c) * 65 + n;
;         u32x4 o; o.x = cvtpk(s[0 * 65] * g0[0], s[1 * 65] * g0[1]); o.y = cvtpk(s[2 * 65] * g0[2], s[3 * 65] * g0[3]); o.z = cvtpk(s[4 * 65] * g1[0], s[5 * 65] * g1[1]); o.w = cvtpk(s[6 * 65] * g1[2], s[7 * 65] * g1[3]);
;         *(u32x4*)(WT + (size_t)(drow0 + n) * K + k0 + 8 * c) = o; }
	v_pk_mul_f32 v[62:63], v[62:63], v[82:83] op_sel:[0,1] op_sel_hi:[1,1]
	v_pk_mul_f32 v[64:65], v[64:65], v[82:83] op_sel:[0,1] op_sel_hi:[1,1]
	v_cvt_pk_bf16_f32 v96, v2, v6
	v_cvt_pk_bf16_f32 v97, v10, v14
	v_cvt_pk_bf16_f32 v98, v18, v22
	v_cvt_pk_bf16_f32 v99, v26, v30
	v_cvt_pk_bf16_f32 v112, v34, v38
	v_cvt_pk_bf16_f32 v113, v42, v46
	v_cvt_pk_bf16_f32 v114, v50, v54
	v_cvt_pk_bf16_f32 v115, v58, v62
	v_mov_b32_dpp v128, v96 row_half_mirror row_mask:0xf bank_mask:0x5
	v_mov_b32_dpp v129, v97 row_half_mirror row_mask:0xf bank_mask:0x5
	v_mov_b32_dpp v130, v98 row_half_mirror row_mask:0xf bank_mask:0x5
	v_mov_b32_dpp v131, v99 row_half_mirror row_mask:0xf bank_mask:0x5
	v_mov_b32_dpp v128, v112 quad_perm:[0,1,2,3] row_mask:0xf bank_mask:0xa
	v_mov_b32_dpp v129, v113 quad_perm:[0,1,2,3] row_mask:0xf bank_mask:0xa
	v_mov_b32_dpp v130, v114 quad_perm:[0,1,2,3] row_mask:0xf bank_mask:0xa
	v_mov_b32_dpp v131, v115 quad_perm:[0,1,2,3] row_mask:0xf bank_mask:0xa
	v_mov_b32_dpp v96, v112 row_half_mirror row_mask:0xf bank_mask:0xa
	v_mov_b32_dpp v97, v113 row_half_mirror row_mask:0xf bank_mask:0xa
	v_mov_b32_dpp v98, v114 row_half_mirror row_mask:0xf bank_mask:0xa
	v_mov_b32_dpp v99, v115 row_half_mirror row_mask:0xf bank_mask:0xa
	global_store_dwordx4 v84, v[96:99], s[44:45]
	global_store_dwordx4 v95, v[128:131], s[44:45]
	s_add_u32 s44, s44, s6
	s_addc_u32 s45, s45, 0
	v_cvt_pk_bf16_f32 v100, v3, v7
	v_cvt_pk_bf16_f32 v101, v11, v15
	v_cvt_pk_bf16_f32 v102, v19, v23
	v_cvt_pk_bf16_f32 v103, v27, v31
	v_cvt_pk_bf16_f32 v116, v35, v39
	v_cvt_pk_bf16_f32 v117, v43, v47
	v_cvt_pk_bf16_f32 v118, v51, v55
	v_cvt_pk_bf16_f32 v119, v59, v63
	v_mov_b32_dpp v132, v100 row_half_mirror row_mask:0xf bank_mask:0x5
	v_mov_b32_dpp v133, v101 row_half_mirror row_mask:0xf bank_mask:0x5
	v_mov_b32_dpp v134, v102 row_half_mirror row_mask:0xf bank_mask:0x5
	v_mov_b32_dpp v135, v103 row_half_mirror row_mask:0xf bank_mask:0x5
	v_mov_b32_dpp v132, v116 quad_perm:[0,1,2,3] row_mask:0xf bank_mask:0xa
	v_mov_b32_dpp v133, v117 quad_perm:[0,1,2,3] row_mask:0xf bank_mask:0xa
	v_mov_b32_dpp v134, v118 quad_perm:[0,1,2,3] row_mask:0xf bank_mask:0xa
	v_mov_b32_dpp v135, v119 quad_perm:[0,1,2,3] row_mask:0xf bank_mask:0xa
	v_mov_b32_dpp v100, v116 row_half_mirror row_mask:0xf bank_mask:0xa
	v_mov_b32_dpp v101, v117 row_half_mirror row_mask:0xf bank_mask:0xa
	v_mov_b32_dpp v102, v118 row_half_mirror row_mask:0xf bank_mask:0xa
	v_mov_b32_dpp v103, v119 row_half_mirror row_mask:0xf bank_mask:0xa
	global_store_dwordx4 v84, v[100:103], s[44:45]
	global_store_dwordx4 v95, v[132:135], s[44:45]
	s_add_u32 s44, s44, s6
	s_addc_u32 s45, s45, 0
	v_cvt_pk_bf16_f32 v104, v4, v8
	v_cvt_pk_bf16_f32 v105, v12, v16
	v_cvt_pk_bf16_f32 v106, v20, v24
	v_cvt_pk_bf16_f32 v107, v28, v32
	v_cvt_pk_bf16_f32 v120, v36, v40
	v_cvt_pk_bf16_f32 v121, v44, v48
	v_cvt_pk_bf16_f32 v122, v52, v56
	v_cvt_pk_bf16_f32 v123, v60, v64
	v_mov_b32_dpp v136, v104 row_half_mirror row_mask:0xf bank_mask:0x5
	v_mov_b32_dpp v137, v105 row_half_mirror row_mask:0xf bank_mask:0x5
	v_mov_b32_dpp v138, v106 row_half_mirror row_mask:0xf bank_mask:0x5
	v_mov_b32_dpp v139, v107 row_half_mirror row_mask:0xf bank_mask:0x5
	v_mov_b32_dpp v136, v120 quad_perm:[0,1,2,3] row_mask:0xf bank_mask:0xa
	v_mov_b32_dpp v137, v121 quad_perm:[0,1,2,3] row_mask:0xf bank_mask:0xa
	v_mov_b32_dpp v138, v122 quad_perm:[0,1,2,3] row_mask:0xf bank_mask:0xa
	v_mov_b32_dpp v139, v123 quad_perm:[0,1,2,3] row_mask:0xf bank_mask:0xa
	v_mov_b32_dpp v104, v120 row_half_mirror row_mask:0xf bank_mask:0xa
	v_mov_b32_dpp v105, v121 row_half_mirror row_mask:0xf bank_mask:0xa
	v_mov_b32_dpp v106, v122 row_half_mirror row_mask:0xf bank_mask:0xa
	v_mov_b32_dpp v107, v123 row_half_mirror row_mask:0xf bank_mask:0xa
	global_store_dwordx4 v84, v[104:107], s[44:45]
	global_store_dwordx4 v95, v[136:139], s[44:45]
	s_add_u32 s44, s44, s6
	s_addc_u32 s45, s45, 0
	v_cvt_pk_bf16_f32 v108, v5, v9
	v_cvt_pk_bf16_f32 v109, v13, v17
	v_cvt_pk_bf16_f32 v110, v21, v25
	v_cvt_pk_bf16_f32 v111, v29, v33
	v_cvt_pk_bf16_f32 v124, v37, v41
	v_cvt_pk_bf16_f32 v125, v45, v49
	v_cvt_pk_bf16_f32 v126, v53, v57
	v_cvt_pk_bf16_f32 v127, v61, v65
	v_mov_b32_dpp v140, v108 row_half_mirror row_mask:0xf bank_mask:0x5
	v_mov_b32_dpp v141, v109 row_half_mirror row_mask:0xf bank_mask:0x5
	v_mov_b32_dpp v142, v110 row_half_mirror row_mask:0xf bank_mask:0x5
	v_mov_b32_dpp v143, v111 row_half_mirror row_mask:0xf bank_mask:0x5
	v_mov_b32_dpp v140, v124 quad_perm:[0,1,2,3] row_mask:0xf bank_mask:0xa
	v_mov_b32_dpp v141, v125 quad_perm:[0,1,2,3] row_mask:0xf bank_mask:0xa
	v_mov_b32_dpp v142, v126 quad_perm:[0,1,2,3] row_mask:0xf bank_mask:0xa
	v_mov_b32_dpp v143, v127 quad_perm:[0,1,2,3] row_mask:0xf bank_mask:0xa
	v_mov_b32_dpp v108, v124 row_half_mirror row_mask:0xf bank_mask:0xa
	v_mov_b32_dpp v109, v125 row_half_mirror row_mask:0xf bank_mask:0xa
	v_mov_b32_dpp v110, v126 row_half_mirror row_mask:0xf bank_mask:0xa
	v_mov_b32_dpp v111, v127 row_half_mirror row_mask:0xf bank_mask:0xa
	global_store_dwordx4 v84, v[108:111], s[44:45]
	global_store_dwordx4 v95, v[140:143], s[44:45]
	s_add_i32 s55, s55, s1
	s_cmpk_gt_i32 s55, 0x567f
	s_cbranch_scc0 .Lp0_loop
